# q-projection rope epilogue: 3-deep software pipelining of the 32 serial cos/sin-load -> rotate -> store steps (loads of later steps issued early into spare registers, counted waits)
# baseline (speedup 1.0000x reference)
; DI u16 f2bf(float x) { return (u16)(pack2(x, 0.f) & 0xffffu); }
; DI int crow(int i, int h) { return (i & 3) + 8 * (i >> 2) + 4 * h; }
; __global__ void __launch_bounds__(256, 2) fwd_megakernel(Params p) {
;     ...
;           if (is_rope) {
; #pragma unroll
;             for (int mt = 0; mt < 2; mt++)
; #pragma unroll
;               for (int i = 0; i < 16; i++) {
;                 const int m = m0 + wm * 64 + mt * 32 + crow(i, h);
;                 const float v0 = acc[mt][0][i], v1 = acc[mt][1][i];
;                 const int pos = tok_pos(m);
;                 const float c = ct[pos * 32 + r], s = st[pos * 32 + r];
;                 Q[(long)m * 1536 + nw0 + r] = f2bf((v0 * c - v1 * s) * QSCALE);
;                 Q[(long)m * 1536 + nw0 + 32 + r] = f2bf((v1 * c + v0 * s) * QSCALE);
;               }
.LBB0_567:
	s_andn2_saveexec_b64 s[52:53], s[0:1]
	s_cbranch_execz .LBB0_548
	v_cmp_gt_i32_e32 vcc, s33, v99
	v_or_b32_e32 v100, 0x400, v100
	s_nop 0
	v_cndmask_b32_e32 v100, v100, v99, vcc
	v_lshl_or_b32 v100, v100, 5, v69
	v_ashrrev_i32_e32 v101, 31, v100
	v_lshlrev_b64 v[100:101], 2, v[100:101]
	v_lshl_add_u64 v[102:103], s[34:35], 0, v[100:101]
	v_lshl_add_u64 v[100:101], s[36:37], 0, v[100:101]
	global_load_dword v228, v[102:103], off
	v_cmp_gt_i32_e32 vcc, s33, v98
	global_load_dword v229, v[100:101], off
	s_waitcnt vmcnt(0)
	v_mul_f32_e32 v100, v50, v229
	v_fma_f32 v100, v34, v228, -v100
	v_mul_f32_e32 v34, v34, v229
	v_mul_f32_e32 v100, 0x3dd53b94, v100
	v_fmac_f32_e32 v34, v50, v228
	v_cvt_pk_bf16_f32 v104, v100, s0
	v_mad_i64_i32 v[100:101], s[0:1], v99, s85, v[66:67]
	v_mul_f32_e32 v34, 0x3dd53b94, v34
	s_nop 0
	v_cvt_pk_bf16_f32 v34, v34, s0
	global_store_short v[100:101], v34, off offset:64
	v_and_or_b32 v34, v98, 5, v210
	v_cndmask_b32_e32 v34, v34, v98, vcc
	global_store_short v[100:101], v104, off
	v_lshl_or_b32 v100, v34, 5, v69
	v_ashrrev_i32_e32 v101, 31, v100
	v_lshlrev_b64 v[100:101], 2, v[100:101]
	v_lshl_add_u64 v[102:103], s[34:35], 0, v[100:101]
	v_lshl_add_u64 v[100:101], s[36:37], 0, v[100:101]
	global_load_dword v34, v[102:103], off
	global_load_dword v50, v[100:101], off
	v_cmp_gt_i32_e32 vcc, s33, v97
	s_waitcnt vmcnt(0)
	v_mul_f32_e32 v99, v51, v50
	v_fma_f32 v99, v35, v34, -v99
	v_mul_f32_e32 v35, v35, v50
	v_mul_f32_e32 v99, 0x3dd53b94, v99
	v_fmac_f32_e32 v35, v51, v34
	v_cvt_pk_bf16_f32 v100, v99, s0
	v_mad_i64_i32 v[98:99], s[0:1], v98, s85, v[66:67]
	v_mul_f32_e32 v34, 0x3dd53b94, v35
	s_nop 0
	v_cvt_pk_bf16_f32 v34, v34, s0
	global_store_short v[98:99], v34, off offset:64
	v_and_or_b32 v34, v97, 6, v210
	v_cndmask_b32_e32 v34, v34, v97, vcc
	v_lshl_or_b32 v34, v34, 5, v69
	v_ashrrev_i32_e32 v35, 31, v34
	v_lshlrev_b64 v[34:35], 2, v[34:35]
	v_lshl_add_u64 v[50:51], s[34:35], 0, v[34:35]
	v_lshl_add_u64 v[34:35], s[36:37], 0, v[34:35]
	global_load_dword v50, v[50:51], off
	v_cmp_gt_i32_e32 vcc, s33, v96
	global_load_dword v51, v[34:35], off
	s_waitcnt vmcnt(0)
	v_mul_f32_e32 v34, v52, v51
	v_fma_f32 v34, v36, v50, -v34
	v_mul_f32_e32 v36, v36, v51
	v_mul_f32_e32 v34, 0x3dd53b94, v34
	v_fmac_f32_e32 v36, v52, v50
	global_store_short v[98:99], v100, off
	v_cvt_pk_bf16_f32 v98, v34, s0
	v_mad_i64_i32 v[34:35], s[0:1], v97, s85, v[66:67]
	v_mul_f32_e32 v36, 0x3dd53b94, v36
	s_nop 0
	v_cvt_pk_bf16_f32 v36, v36, s0
	global_store_short v[34:35], v98, off
	global_store_short v[34:35], v36, off offset:64
	v_and_or_b32 v34, v96, 7, v210
	v_cndmask_b32_e32 v34, v34, v96, vcc
	v_lshl_or_b32 v34, v34, 5, v69
	v_ashrrev_i32_e32 v35, 31, v34
	v_lshlrev_b64 v[34:35], 2, v[34:35]
	v_lshl_add_u64 v[50:51], s[34:35], 0, v[34:35]
	v_lshl_add_u64 v[34:35], s[36:37], 0, v[34:35]
	global_load_dword v36, v[50:51], off
	v_cmp_gt_i32_e32 vcc, s33, v95
	global_load_dword v50, v[34:35], off
	s_waitcnt vmcnt(0)
	v_mul_f32_e32 v34, v53, v50
	v_fma_f32 v34, v37, v36, -v34
	v_mul_f32_e32 v37, v37, v50
	v_mul_f32_e32 v34, 0x3dd53b94, v34
	v_fmac_f32_e32 v37, v53, v36
	v_cvt_pk_bf16_f32 v51, v34, s0
	v_mad_i64_i32 v[34:35], s[0:1], v96, s85, v[66:67]
	v_mul_f32_e32 v36, 0x3dd53b94, v37
	s_nop 0
	v_cvt_pk_bf16_f32 v36, v36, s0
	global_store_short v[34:35], v51, off
	global_store_short v[34:35], v36, off offset:64
	v_and_or_b32 v34, v95, 12, v210
	v_cndmask_b32_e32 v34, v34, v95, vcc
	v_lshl_or_b32 v34, v34, 5, v69
	v_ashrrev_i32_e32 v35, 31, v34
	v_lshlrev_b64 v[34:35], 2, v[34:35]
	v_lshl_add_u64 v[36:37], s[34:35], 0, v[34:35]
	v_lshl_add_u64 v[34:35], s[36:37], 0, v[34:35]
	global_load_dword v228, v[36:37], off
	v_cmp_gt_i32_e32 vcc, s33, v94
	global_load_dword v229, v[34:35], off
	v_and_or_b32 v34, v94, 13, v210
	v_cndmask_b32_e32 v34, v34, v94, vcc
	v_lshl_or_b32 v34, v34, 5, v69
	v_ashrrev_i32_e32 v35, 31, v34
	v_lshlrev_b64 v[34:35], 2, v[34:35]
	v_lshl_add_u64 v[36:37], s[34:35], 0, v[34:35]
	v_lshl_add_u64 v[34:35], s[36:37], 0, v[34:35]
	global_load_dword v230, v[36:37], off
	v_cmp_gt_i32_e32 vcc, s33, v93
	global_load_dword v231, v[34:35], off
	v_and_or_b32 v34, v93, 14, v210
	v_cndmask_b32_e32 v34, v34, v93, vcc
	v_lshl_or_b32 v34, v34, 5, v69
	v_ashrrev_i32_e32 v35, 31, v34
	v_lshlrev_b64 v[34:35], 2, v[34:35]
	v_lshl_add_u64 v[36:37], s[34:35], 0, v[34:35]
	v_lshl_add_u64 v[34:35], s[36:37], 0, v[34:35]
	global_load_dword v232, v[36:37], off
	v_cmp_gt_i32_e32 vcc, s33, v92
	global_load_dword v233, v[34:35], off
	s_waitcnt vmcnt(4)
	v_mul_f32_e32 v34, v54, v229
	v_fma_f32 v34, v38, v228, -v34
	v_mul_f32_e32 v37, v38, v229
	v_mul_f32_e32 v34, 0x3dd53b94, v34
	v_fmac_f32_e32 v37, v54, v228
	v_cvt_pk_bf16_f32 v50, v34, s0
	v_mad_i64_i32 v[34:35], s[0:1], v95, s85, v[66:67]
	v_mul_f32_e32 v36, 0x3dd53b94, v37
	s_nop 0
	v_cvt_pk_bf16_f32 v36, v36, s0
	global_store_short v[34:35], v50, off
	global_store_short v[34:35], v36, off offset:64
	v_and_or_b32 v34, v92, 15, v210
	v_cndmask_b32_e32 v34, v34, v92, vcc
	v_lshl_or_b32 v34, v34, 5, v69
	v_ashrrev_i32_e32 v35, 31, v34
	v_lshlrev_b64 v[34:35], 2, v[34:35]
	v_lshl_add_u64 v[36:37], s[34:35], 0, v[34:35]
	v_lshl_add_u64 v[34:35], s[36:37], 0, v[34:35]
	global_load_dword v228, v[36:37], off
	v_cmp_gt_i32_e32 vcc, s33, v91
	global_load_dword v229, v[34:35], off
	s_waitcnt vmcnt(6)
; DI u16 f2bf(float x) { return (u16)(pack2(x, 0.f) & 0xffffu); }
; DI int crow(int i, int h) { return (i & 3) + 8 * (i >> 2) + 4 * h; }
; __global__ void __launch_bounds__(256, 2) fwd_megakernel(Params p) {
;     ...
;           if (is_rope) {
; #pragma unroll
;             for (int mt = 0; mt < 2; mt++)
; #pragma unroll
;               for (int i = 0; i < 16; i++) {
;                 const int m = m0 + wm * 64 + mt * 32 + crow(i, h);
;                 const float v0 = acc[mt][0][i], v1 = acc[mt][1][i];
;                 const int pos = tok_pos(m);
;                 const float c = ct[pos * 32 + r], s = st[pos * 32 + r];
;                 Q[(long)m * 1536 + nw0 + r] = f2bf((v0 * c - v1 * s) * QSCALE);
;                 Q[(long)m * 1536 + nw0 + 32 + r] = f2bf((v1 * c + v0 * s) * QSCALE);
;               }
	v_mul_f32_e32 v34, v55, v231
	v_fma_f32 v34, v39, v230, -v34
	v_mul_f32_e32 v37, v39, v231
	v_mul_f32_e32 v34, 0x3dd53b94, v34
	v_fmac_f32_e32 v37, v55, v230
	v_cvt_pk_bf16_f32 v38, v34, s0
	v_mad_i64_i32 v[34:35], s[0:1], v94, s85, v[66:67]
	v_mul_f32_e32 v36, 0x3dd53b94, v37
	s_nop 0
	v_cvt_pk_bf16_f32 v36, v36, s0
	global_store_short v[34:35], v38, off
	global_store_short v[34:35], v36, off offset:64
	v_and_or_b32 v34, v91, 20, v210
	v_cndmask_b32_e32 v34, v34, v91, vcc
	v_lshl_or_b32 v34, v34, 5, v69
	v_ashrrev_i32_e32 v35, 31, v34
	v_lshlrev_b64 v[34:35], 2, v[34:35]
	v_lshl_add_u64 v[36:37], s[34:35], 0, v[34:35]
	v_lshl_add_u64 v[34:35], s[36:37], 0, v[34:35]
	global_load_dword v230, v[36:37], off
	v_cmp_gt_i32_e32 vcc, s33, v90
	global_load_dword v231, v[34:35], off
	s_waitcnt vmcnt(8)
	v_mul_f32_e32 v34, v56, v233
	v_fma_f32 v34, v40, v232, -v34
	v_mul_f32_e32 v37, v40, v233
	v_mul_f32_e32 v34, 0x3dd53b94, v34
	v_fmac_f32_e32 v37, v56, v232
	v_cvt_pk_bf16_f32 v38, v34, s0
	v_mad_i64_i32 v[34:35], s[0:1], v93, s85, v[66:67]
	v_mul_f32_e32 v36, 0x3dd53b94, v37
	s_nop 0
	v_cvt_pk_bf16_f32 v36, v36, s0
	global_store_short v[34:35], v38, off
	global_store_short v[34:35], v36, off offset:64
	v_and_or_b32 v34, v90, 21, v210
	v_cndmask_b32_e32 v34, v34, v90, vcc
	v_lshl_or_b32 v34, v34, 5, v69
	v_ashrrev_i32_e32 v35, 31, v34
	v_lshlrev_b64 v[34:35], 2, v[34:35]
	v_lshl_add_u64 v[36:37], s[34:35], 0, v[34:35]
	v_lshl_add_u64 v[34:35], s[36:37], 0, v[34:35]
	global_load_dword v232, v[36:37], off
	v_cmp_gt_i32_e32 vcc, s33, v89
	global_load_dword v233, v[34:35], off
	s_waitcnt vmcnt(8)
	v_mul_f32_e32 v34, v57, v229
	v_fma_f32 v34, v41, v228, -v34
	v_mul_f32_e32 v37, v41, v229
	v_mul_f32_e32 v34, 0x3dd53b94, v34
	v_fmac_f32_e32 v37, v57, v228
	v_cvt_pk_bf16_f32 v38, v34, s0
	v_mad_i64_i32 v[34:35], s[0:1], v92, s85, v[66:67]
	v_mul_f32_e32 v36, 0x3dd53b94, v37
	s_nop 0
	v_cvt_pk_bf16_f32 v36, v36, s0
	global_store_short v[34:35], v38, off
	global_store_short v[34:35], v36, off offset:64
	v_and_or_b32 v34, v89, 22, v210
	v_cndmask_b32_e32 v34, v34, v89, vcc
	v_lshl_or_b32 v34, v34, 5, v69
	v_ashrrev_i32_e32 v35, 31, v34
	v_lshlrev_b64 v[34:35], 2, v[34:35]
	v_lshl_add_u64 v[36:37], s[34:35], 0, v[34:35]
	v_lshl_add_u64 v[34:35], s[36:37], 0, v[34:35]
	global_load_dword v228, v[36:37], off
	v_cmp_gt_i32_e32 vcc, s33, v88
	global_load_dword v229, v[34:35], off
	s_waitcnt vmcnt(8)
	v_mul_f32_e32 v34, v58, v231
	v_fma_f32 v34, v42, v230, -v34
	v_mul_f32_e32 v37, v42, v231
	v_mul_f32_e32 v34, 0x3dd53b94, v34
	v_fmac_f32_e32 v37, v58, v230
	v_cvt_pk_bf16_f32 v38, v34, s0
	v_mad_i64_i32 v[34:35], s[0:1], v91, s85, v[66:67]
	v_mul_f32_e32 v36, 0x3dd53b94, v37
	s_nop 0
	v_cvt_pk_bf16_f32 v36, v36, s0
	global_store_short v[34:35], v38, off
	global_store_short v[34:35], v36, off offset:64
	v_and_or_b32 v34, v88, 23, v210
	v_cndmask_b32_e32 v34, v34, v88, vcc
	v_lshl_or_b32 v34, v34, 5, v69
	v_ashrrev_i32_e32 v35, 31, v34
	v_lshlrev_b64 v[34:35], 2, v[34:35]
	v_lshl_add_u64 v[36:37], s[34:35], 0, v[34:35]
	v_lshl_add_u64 v[34:35], s[36:37], 0, v[34:35]
	global_load_dword v230, v[36:37], off
	v_cmp_gt_i32_e32 vcc, s33, v87
	global_load_dword v231, v[34:35], off
	s_waitcnt vmcnt(8)
	v_mul_f32_e32 v34, v59, v233
	v_fma_f32 v34, v43, v232, -v34
	v_mul_f32_e32 v37, v43, v233
	v_mul_f32_e32 v34, 0x3dd53b94, v34
	v_fmac_f32_e32 v37, v59, v232
	v_cvt_pk_bf16_f32 v38, v34, s0
	v_mad_i64_i32 v[34:35], s[0:1], v90, s85, v[66:67]
	v_mul_f32_e32 v36, 0x3dd53b94, v37
	s_nop 0
	v_cvt_pk_bf16_f32 v36, v36, s0
	global_store_short v[34:35], v38, off
	global_store_short v[34:35], v36, off offset:64
	v_and_or_b32 v34, v87, 28, v210
	v_cndmask_b32_e32 v34, v34, v87, vcc
	v_lshl_or_b32 v34, v34, 5, v69
	v_ashrrev_i32_e32 v35, 31, v34
	v_lshlrev_b64 v[34:35], 2, v[34:35]
	v_lshl_add_u64 v[36:37], s[34:35], 0, v[34:35]
	v_lshl_add_u64 v[34:35], s[36:37], 0, v[34:35]
	global_load_dword v232, v[36:37], off
	v_cmp_gt_i32_e32 vcc, s33, v86
	global_load_dword v233, v[34:35], off
	s_waitcnt vmcnt(8)
	v_mul_f32_e32 v34, v60, v229
	v_fma_f32 v34, v44, v228, -v34
	v_mul_f32_e32 v37, v44, v229
	v_mul_f32_e32 v34, 0x3dd53b94, v34
	v_fmac_f32_e32 v37, v60, v228
	v_cvt_pk_bf16_f32 v38, v34, s0
	v_mad_i64_i32 v[34:35], s[0:1], v89, s85, v[66:67]
	v_mul_f32_e32 v36, 0x3dd53b94, v37
	s_nop 0
	v_cvt_pk_bf16_f32 v36, v36, s0
	global_store_short v[34:35], v38, off
	global_store_short v[34:35], v36, off offset:64
	v_and_or_b32 v34, v86, 29, v210
	v_cndmask_b32_e32 v34, v34, v86, vcc
	v_lshl_or_b32 v34, v34, 5, v69
	v_ashrrev_i32_e32 v35, 31, v34
	v_lshlrev_b64 v[34:35], 2, v[34:35]
	v_lshl_add_u64 v[36:37], s[34:35], 0, v[34:35]
	v_lshl_add_u64 v[34:35], s[36:37], 0, v[34:35]
	global_load_dword v228, v[36:37], off
	v_cmp_gt_i32_e32 vcc, s33, v85
	global_load_dword v229, v[34:35], off
	s_waitcnt vmcnt(8)
	v_mul_f32_e32 v34, v61, v231
	v_fma_f32 v34, v45, v230, -v34
	v_mul_f32_e32 v37, v45, v231
	v_mul_f32_e32 v34, 0x3dd53b94, v34
	v_fmac_f32_e32 v37, v61, v230
	v_cvt_pk_bf16_f32 v38, v34, s0
	v_mad_i64_i32 v[34:35], s[0:1], v88, s85, v[66:67]
	v_mul_f32_e32 v36, 0x3dd53b94, v37
	s_nop 0
	v_cvt_pk_bf16_f32 v36, v36, s0
	global_store_short v[34:35], v38, off
	global_store_short v[34:35], v36, off offset:64
	v_and_or_b32 v34, v85, 30, v210
	v_cndmask_b32_e32 v34, v34, v85, vcc
	v_lshl_or_b32 v34, v34, 5, v69
	v_ashrrev_i32_e32 v35, 31, v34
	v_lshlrev_b64 v[34:35], 2, v[34:35]
	v_lshl_add_u64 v[36:37], s[34:35], 0, v[34:35]
	v_lshl_add_u64 v[34:35], s[36:37], 0, v[34:35]
	global_load_dword v230, v[36:37], off
	v_cmp_gt_i32_e32 vcc, s33, v84
	global_load_dword v231, v[34:35], off
	s_waitcnt vmcnt(8)
; DI u16 f2bf(float x) { return (u16)(pack2(x, 0.f) & 0xffffu); }
; DI int crow(int i, int h) { return (i & 3) + 8 * (i >> 2) + 4 * h; }
; __global__ void __launch_bounds__(256, 2) fwd_megakernel(Params p) {
;     ...
;           if (is_rope) {
; #pragma unroll
;             for (int mt = 0; mt < 2; mt++)
; #pragma unroll
;               for (int i = 0; i < 16; i++) {
;                 const int m = m0 + wm * 64 + mt * 32 + crow(i, h);
;                 const float v0 = acc[mt][0][i], v1 = acc[mt][1][i];
;                 const int pos = tok_pos(m);
;                 const float c = ct[pos * 32 + r], s = st[pos * 32 + r];
;                 Q[(long)m * 1536 + nw0 + r] = f2bf((v0 * c - v1 * s) * QSCALE);
;                 Q[(long)m * 1536 + nw0 + 32 + r] = f2bf((v1 * c + v0 * s) * QSCALE);
;               }
	v_mul_f32_e32 v34, v62, v233
	v_fma_f32 v34, v46, v232, -v34
	v_mul_f32_e32 v37, v46, v233
	v_mul_f32_e32 v34, 0x3dd53b94, v34
	v_fmac_f32_e32 v37, v62, v232
	v_cvt_pk_bf16_f32 v38, v34, s0
	v_mad_i64_i32 v[34:35], s[0:1], v87, s85, v[66:67]
	v_mul_f32_e32 v36, 0x3dd53b94, v37
	s_nop 0
	v_cvt_pk_bf16_f32 v36, v36, s0
	global_store_short v[34:35], v38, off
	global_store_short v[34:35], v36, off offset:64
	v_and_or_b32 v34, v84, 31, v210
	v_cndmask_b32_e32 v34, v34, v84, vcc
	v_lshl_or_b32 v34, v34, 5, v69
	v_ashrrev_i32_e32 v35, 31, v34
	v_lshlrev_b64 v[34:35], 2, v[34:35]
	v_lshl_add_u64 v[36:37], s[34:35], 0, v[34:35]
	v_lshl_add_u64 v[34:35], s[36:37], 0, v[34:35]
	global_load_dword v232, v[36:37], off
	v_cmp_gt_i32_e32 vcc, s33, v83
	global_load_dword v233, v[34:35], off
	s_waitcnt vmcnt(8)
	v_mul_f32_e32 v34, v63, v229
	v_fma_f32 v34, v47, v228, -v34
	v_mul_f32_e32 v37, v47, v229
	v_mul_f32_e32 v34, 0x3dd53b94, v34
	v_fmac_f32_e32 v37, v63, v228
	v_cvt_pk_bf16_f32 v38, v34, s0
	v_mad_i64_i32 v[34:35], s[0:1], v86, s85, v[66:67]
	v_mul_f32_e32 v36, 0x3dd53b94, v37
	s_nop 0
	v_cvt_pk_bf16_f32 v36, v36, s0
	global_store_short v[34:35], v38, off
	global_store_short v[34:35], v36, off offset:64
	v_and_or_b32 v34, v83, 36, v210
	v_cndmask_b32_e32 v34, v34, v83, vcc
	v_lshl_or_b32 v34, v34, 5, v69
	v_ashrrev_i32_e32 v35, 31, v34
	v_lshlrev_b64 v[34:35], 2, v[34:35]
	v_lshl_add_u64 v[36:37], s[34:35], 0, v[34:35]
	v_lshl_add_u64 v[34:35], s[36:37], 0, v[34:35]
	global_load_dword v228, v[36:37], off
	v_cmp_gt_i32_e32 vcc, s33, v82
	global_load_dword v229, v[34:35], off
	s_waitcnt vmcnt(8)
	v_mul_f32_e32 v34, v64, v231
	v_fma_f32 v34, v48, v230, -v34
	v_mul_f32_e32 v37, v48, v231
	v_mul_f32_e32 v34, 0x3dd53b94, v34
	v_fmac_f32_e32 v37, v64, v230
	v_cvt_pk_bf16_f32 v38, v34, s0
	v_mad_i64_i32 v[34:35], s[0:1], v85, s85, v[66:67]
	v_mul_f32_e32 v36, 0x3dd53b94, v37
	s_nop 0
	v_cvt_pk_bf16_f32 v36, v36, s0
	global_store_short v[34:35], v38, off
	global_store_short v[34:35], v36, off offset:64
	s_waitcnt vmcnt(6)
	v_mul_f32_e32 v34, v65, v233
	v_fma_f32 v34, v49, v232, -v34
	v_mul_f32_e32 v37, v49, v233
	v_mul_f32_e32 v34, 0x3dd53b94, v34
	v_fmac_f32_e32 v37, v65, v232
	v_cvt_pk_bf16_f32 v38, v34, s0
	v_mad_i64_i32 v[34:35], s[0:1], v84, s85, v[66:67]
	v_mul_f32_e32 v36, 0x3dd53b94, v37
	s_nop 0
	v_cvt_pk_bf16_f32 v36, v36, s0
	global_store_short v[34:35], v38, off
	global_store_short v[34:35], v36, off offset:64
	s_waitcnt vmcnt(4)
	v_mul_f32_e32 v34, v2, v229
	v_fma_f32 v34, v18, v228, -v34
	v_mul_f32_e32 v18, v18, v229
	v_mul_f32_e32 v34, 0x3dd53b94, v34
	v_fmac_f32_e32 v18, v2, v228
	v_cvt_pk_bf16_f32 v38, v34, s0
	v_mad_i64_i32 v[34:35], s[0:1], v83, s85, v[66:67]
	v_mul_f32_e32 v2, 0x3dd53b94, v18
	s_nop 0
	v_cvt_pk_bf16_f32 v2, v2, s0
	global_store_short v[34:35], v2, off offset:64
	v_and_or_b32 v2, v82, 37, v210
	v_cndmask_b32_e32 v2, v2, v82, vcc
	global_store_short v[34:35], v38, off
	v_lshl_or_b32 v34, v2, 5, v69
	v_ashrrev_i32_e32 v35, 31, v34
	v_lshlrev_b64 v[34:35], 2, v[34:35]
	v_lshl_add_u64 v[36:37], s[34:35], 0, v[34:35]
	v_lshl_add_u64 v[34:35], s[36:37], 0, v[34:35]
	global_load_dword v2, v[36:37], off
	global_load_dword v18, v[34:35], off
	v_cmp_gt_i32_e32 vcc, s33, v81
	s_waitcnt vmcnt(0)
	v_mul_f32_e32 v34, v3, v18
	v_fma_f32 v34, v19, v2, -v34
	v_mul_f32_e32 v18, v19, v18
	v_mul_f32_e32 v34, 0x3dd53b94, v34
	v_fmac_f32_e32 v18, v3, v2
	v_cvt_pk_bf16_f32 v36, v34, s0
	v_mad_i64_i32 v[34:35], s[0:1], v82, s85, v[66:67]
	v_mul_f32_e32 v2, 0x3dd53b94, v18
	s_nop 0
	v_cvt_pk_bf16_f32 v2, v2, s0
	global_store_short v[34:35], v2, off offset:64
	v_and_or_b32 v2, v81, 38, v210
	v_cndmask_b32_e32 v2, v2, v81, vcc
	v_lshl_or_b32 v2, v2, 5, v69
	v_ashrrev_i32_e32 v3, 31, v2
	v_lshlrev_b64 v[2:3], 2, v[2:3]
	v_lshl_add_u64 v[18:19], s[34:35], 0, v[2:3]
	v_lshl_add_u64 v[2:3], s[36:37], 0, v[2:3]
	global_load_dword v18, v[18:19], off
	v_cmp_gt_i32_e32 vcc, s33, v80
	global_load_dword v19, v[2:3], off
	s_waitcnt vmcnt(0)
	v_mul_f32_e32 v2, v4, v19
	v_fma_f32 v2, v20, v18, -v2
	v_mul_f32_e32 v19, v20, v19
	v_mul_f32_e32 v2, 0x3dd53b94, v2
	v_fmac_f32_e32 v19, v4, v18
	global_store_short v[34:35], v36, off
	v_cvt_pk_bf16_f32 v34, v2, s0
	v_mad_i64_i32 v[2:3], s[0:1], v81, s85, v[66:67]
	v_mul_f32_e32 v4, 0x3dd53b94, v19
	s_nop 0
	v_cvt_pk_bf16_f32 v4, v4, s0
	global_store_short v[2:3], v34, off
	global_store_short v[2:3], v4, off offset:64
	v_and_or_b32 v2, v80, 39, v210
	v_cndmask_b32_e32 v2, v2, v80, vcc
	v_lshl_or_b32 v2, v2, 5, v69
	v_ashrrev_i32_e32 v3, 31, v2
	v_lshlrev_b64 v[2:3], 2, v[2:3]
	v_lshl_add_u64 v[18:19], s[34:35], 0, v[2:3]
	v_lshl_add_u64 v[2:3], s[36:37], 0, v[2:3]
	global_load_dword v4, v[18:19], off
	v_cmp_gt_i32_e32 vcc, s33, v79
	global_load_dword v18, v[2:3], off
	s_waitcnt vmcnt(0)
	v_mul_f32_e32 v2, v5, v18
	v_fma_f32 v2, v21, v4, -v2
	v_mul_f32_e32 v18, v21, v18
	v_mul_f32_e32 v2, 0x3dd53b94, v2
	v_fmac_f32_e32 v18, v5, v4
	v_cvt_pk_bf16_f32 v19, v2, s0
	v_mad_i64_i32 v[2:3], s[0:1], v80, s85, v[66:67]
	v_mul_f32_e32 v4, 0x3dd53b94, v18
	s_nop 0
	v_cvt_pk_bf16_f32 v4, v4, s0
	global_store_short v[2:3], v19, off
	global_store_short v[2:3], v4, off offset:64
	v_and_or_b32 v2, v79, 44, v210
	v_cndmask_b32_e32 v2, v2, v79, vcc
	v_lshl_or_b32 v2, v2, 5, v69
	v_ashrrev_i32_e32 v3, 31, v2
	v_lshlrev_b64 v[2:3], 2, v[2:3]
	v_lshl_add_u64 v[4:5], s[34:35], 0, v[2:3]
	v_lshl_add_u64 v[2:3], s[36:37], 0, v[2:3]
	global_load_dword v228, v[4:5], off
	v_cmp_gt_i32_e32 vcc, s33, v78
	global_load_dword v229, v[2:3], off
	v_and_or_b32 v2, v78, 45, v210
	v_cndmask_b32_e32 v2, v2, v78, vcc
	v_lshl_or_b32 v2, v2, 5, v69
	v_ashrrev_i32_e32 v3, 31, v2
	v_lshlrev_b64 v[2:3], 2, v[2:3]
	v_lshl_add_u64 v[4:5], s[34:35], 0, v[2:3]
	v_lshl_add_u64 v[2:3], s[36:37], 0, v[2:3]
	global_load_dword v230, v[4:5], off
	v_cmp_gt_i32_e32 vcc, s33, v77
	global_load_dword v231, v[2:3], off
	v_and_or_b32 v2, v77, 46, v210
	v_cndmask_b32_e32 v2, v2, v77, vcc
	v_lshl_or_b32 v2, v2, 5, v69
	v_ashrrev_i32_e32 v3, 31, v2
	v_lshlrev_b64 v[2:3], 2, v[2:3]
	v_lshl_add_u64 v[4:5], s[34:35], 0, v[2:3]
	v_lshl_add_u64 v[2:3], s[36:37], 0, v[2:3]
	global_load_dword v232, v[4:5], off
	v_cmp_gt_i32_e32 vcc, s33, v76
	global_load_dword v233, v[2:3], off
	s_waitcnt vmcnt(4)
; DI u16 f2bf(float x) { return (u16)(pack2(x, 0.f) & 0xffffu); }
; DI int crow(int i, int h) { return (i & 3) + 8 * (i >> 2) + 4 * h; }
; __global__ void __launch_bounds__(256, 2) fwd_megakernel(Params p) {
;     ...
;           if (is_rope) {
; #pragma unroll
;             for (int mt = 0; mt < 2; mt++)
; #pragma unroll
;               for (int i = 0; i < 16; i++) {
;                 const int m = m0 + wm * 64 + mt * 32 + crow(i, h);
;                 const float v0 = acc[mt][0][i], v1 = acc[mt][1][i];
;                 const int pos = tok_pos(m);
;                 const float c = ct[pos * 32 + r], s = st[pos * 32 + r];
;                 Q[(long)m * 1536 + nw0 + r] = f2bf((v0 * c - v1 * s) * QSCALE);
;                 Q[(long)m * 1536 + nw0 + 32 + r] = f2bf((v1 * c + v0 * s) * QSCALE);
;               }
	v_mul_f32_e32 v2, v6, v229
	v_fma_f32 v2, v22, v228, -v2
	v_mul_f32_e32 v5, v22, v229
	v_mul_f32_e32 v2, 0x3dd53b94, v2
	v_fmac_f32_e32 v5, v6, v228
	v_cvt_pk_bf16_f32 v18, v2, s0
	v_mad_i64_i32 v[2:3], s[0:1], v79, s85, v[66:67]
	v_mul_f32_e32 v4, 0x3dd53b94, v5
	s_nop 0
	v_cvt_pk_bf16_f32 v4, v4, s0
	global_store_short v[2:3], v18, off
	global_store_short v[2:3], v4, off offset:64
	v_and_or_b32 v2, v76, 47, v210
	v_cndmask_b32_e32 v2, v2, v76, vcc
	v_lshl_or_b32 v2, v2, 5, v69
	v_ashrrev_i32_e32 v3, 31, v2
	v_lshlrev_b64 v[2:3], 2, v[2:3]
	v_lshl_add_u64 v[4:5], s[34:35], 0, v[2:3]
	v_lshl_add_u64 v[2:3], s[36:37], 0, v[2:3]
	global_load_dword v228, v[4:5], off
	v_cmp_gt_i32_e32 vcc, s33, v75
	global_load_dword v229, v[2:3], off
	s_waitcnt vmcnt(6)
	v_mul_f32_e32 v2, v7, v231
	v_fma_f32 v2, v23, v230, -v2
	v_mul_f32_e32 v5, v23, v231
	v_mul_f32_e32 v2, 0x3dd53b94, v2
	v_fmac_f32_e32 v5, v7, v230
	v_cvt_pk_bf16_f32 v6, v2, s0
	v_mad_i64_i32 v[2:3], s[0:1], v78, s85, v[66:67]
	v_mul_f32_e32 v4, 0x3dd53b94, v5
	s_nop 0
	v_cvt_pk_bf16_f32 v4, v4, s0
	global_store_short v[2:3], v6, off
	global_store_short v[2:3], v4, off offset:64
	v_and_or_b32 v2, v75, 52, v210
	v_cndmask_b32_e32 v2, v2, v75, vcc
	v_lshl_or_b32 v2, v2, 5, v69
	v_ashrrev_i32_e32 v3, 31, v2
	v_lshlrev_b64 v[2:3], 2, v[2:3]
	v_lshl_add_u64 v[4:5], s[34:35], 0, v[2:3]
	v_lshl_add_u64 v[2:3], s[36:37], 0, v[2:3]
	global_load_dword v230, v[4:5], off
	v_cmp_gt_i32_e32 vcc, s33, v74
	global_load_dword v231, v[2:3], off
	s_waitcnt vmcnt(8)
	v_mul_f32_e32 v2, v8, v233
	v_fma_f32 v2, v24, v232, -v2
	v_mul_f32_e32 v5, v24, v233
	v_mul_f32_e32 v2, 0x3dd53b94, v2
	v_fmac_f32_e32 v5, v8, v232
	v_cvt_pk_bf16_f32 v6, v2, s0
	v_mad_i64_i32 v[2:3], s[0:1], v77, s85, v[66:67]
	v_mul_f32_e32 v4, 0x3dd53b94, v5
	s_nop 0
	v_cvt_pk_bf16_f32 v4, v4, s0
	global_store_short v[2:3], v6, off
	global_store_short v[2:3], v4, off offset:64
	v_and_or_b32 v2, v74, 53, v210
	v_cndmask_b32_e32 v2, v2, v74, vcc
	v_lshl_or_b32 v2, v2, 5, v69
	v_ashrrev_i32_e32 v3, 31, v2
	v_lshlrev_b64 v[2:3], 2, v[2:3]
	v_lshl_add_u64 v[4:5], s[34:35], 0, v[2:3]
	v_lshl_add_u64 v[2:3], s[36:37], 0, v[2:3]
	global_load_dword v232, v[4:5], off
	v_cmp_gt_i32_e32 vcc, s33, v73
	global_load_dword v233, v[2:3], off
	s_waitcnt vmcnt(8)
	v_mul_f32_e32 v2, v9, v229
	v_fma_f32 v2, v25, v228, -v2
	v_mul_f32_e32 v5, v25, v229
	v_mul_f32_e32 v2, 0x3dd53b94, v2
	v_fmac_f32_e32 v5, v9, v228
	v_cvt_pk_bf16_f32 v6, v2, s0
	v_mad_i64_i32 v[2:3], s[0:1], v76, s85, v[66:67]
	v_mul_f32_e32 v4, 0x3dd53b94, v5
	s_nop 0
	v_cvt_pk_bf16_f32 v4, v4, s0
	global_store_short v[2:3], v6, off
	global_store_short v[2:3], v4, off offset:64
	v_and_or_b32 v2, v73, 54, v210
	v_cndmask_b32_e32 v2, v2, v73, vcc
	v_lshl_or_b32 v2, v2, 5, v69
	v_ashrrev_i32_e32 v3, 31, v2
	v_lshlrev_b64 v[2:3], 2, v[2:3]
	v_lshl_add_u64 v[4:5], s[34:35], 0, v[2:3]
	v_lshl_add_u64 v[2:3], s[36:37], 0, v[2:3]
	global_load_dword v228, v[4:5], off
	v_cmp_gt_i32_e32 vcc, s33, v72
	global_load_dword v229, v[2:3], off
	s_waitcnt vmcnt(8)
	v_mul_f32_e32 v2, v10, v231
	v_fma_f32 v2, v26, v230, -v2
	v_mul_f32_e32 v5, v26, v231
	v_mul_f32_e32 v2, 0x3dd53b94, v2
	v_fmac_f32_e32 v5, v10, v230
	v_cvt_pk_bf16_f32 v6, v2, s0
	v_mad_i64_i32 v[2:3], s[0:1], v75, s85, v[66:67]
	v_mul_f32_e32 v4, 0x3dd53b94, v5
	s_nop 0
	v_cvt_pk_bf16_f32 v4, v4, s0
	global_store_short v[2:3], v6, off
	global_store_short v[2:3], v4, off offset:64
	v_and_or_b32 v2, v72, 55, v210
	v_cndmask_b32_e32 v2, v2, v72, vcc
	v_lshl_or_b32 v2, v2, 5, v69
	v_ashrrev_i32_e32 v3, 31, v2
	v_lshlrev_b64 v[2:3], 2, v[2:3]
	v_lshl_add_u64 v[4:5], s[34:35], 0, v[2:3]
	v_lshl_add_u64 v[2:3], s[36:37], 0, v[2:3]
	global_load_dword v230, v[4:5], off
	v_cmp_gt_i32_e32 vcc, s33, v71
	global_load_dword v231, v[2:3], off
	s_waitcnt vmcnt(8)
; DI u16 f2bf(float x) { return (u16)(pack2(x, 0.f) & 0xffffu); }
; DI int crow(int i, int h) { return (i & 3) + 8 * (i >> 2) + 4 * h; }
; __global__ void __launch_bounds__(256, 2) fwd_megakernel(Params p) {
;     ...
;           if (is_rope) {
; #pragma unroll
;             for (int mt = 0; mt < 2; mt++)
; #pragma unroll
;               for (int i = 0; i < 16; i++) {
;                 const int m = m0 + wm * 64 + mt * 32 + crow(i, h);
;                 const float v0 = acc[mt][0][i], v1 = acc[mt][1][i];
;                 const int pos = tok_pos(m);
;                 const float c = ct[pos * 32 + r], s = st[pos * 32 + r];
;                 Q[(long)m * 1536 + nw0 + r] = f2bf((v0 * c - v1 * s) * QSCALE);
;                 Q[(long)m * 1536 + nw0 + 32 + r] = f2bf((v1 * c + v0 * s) * QSCALE);
;               }
	v_mul_f32_e32 v2, v11, v233
	v_fma_f32 v2, v27, v232, -v2
	v_mul_f32_e32 v5, v27, v233
	v_mul_f32_e32 v2, 0x3dd53b94, v2
	v_fmac_f32_e32 v5, v11, v232
	v_cvt_pk_bf16_f32 v6, v2, s0
	v_mad_i64_i32 v[2:3], s[0:1], v74, s85, v[66:67]
	v_mul_f32_e32 v4, 0x3dd53b94, v5
	s_nop 0
	v_cvt_pk_bf16_f32 v4, v4, s0
	global_store_short v[2:3], v6, off
	global_store_short v[2:3], v4, off offset:64
	v_and_or_b32 v2, v71, 60, v210
	v_cndmask_b32_e32 v2, v2, v71, vcc
	v_lshl_or_b32 v2, v2, 5, v69
	v_ashrrev_i32_e32 v3, 31, v2
	v_lshlrev_b64 v[2:3], 2, v[2:3]
	v_lshl_add_u64 v[4:5], s[34:35], 0, v[2:3]
	v_lshl_add_u64 v[2:3], s[36:37], 0, v[2:3]
	global_load_dword v232, v[4:5], off
	v_cmp_gt_i32_e32 vcc, s33, v70
	global_load_dword v233, v[2:3], off
	s_waitcnt vmcnt(8)
	v_mul_f32_e32 v2, v12, v229
	v_fma_f32 v2, v28, v228, -v2
	v_mul_f32_e32 v5, v28, v229
	v_mul_f32_e32 v2, 0x3dd53b94, v2
	v_fmac_f32_e32 v5, v12, v228
	v_cvt_pk_bf16_f32 v6, v2, s0
	v_mad_i64_i32 v[2:3], s[0:1], v73, s85, v[66:67]
	v_mul_f32_e32 v4, 0x3dd53b94, v5
	s_nop 0
	v_cvt_pk_bf16_f32 v4, v4, s0
	global_store_short v[2:3], v6, off
	global_store_short v[2:3], v4, off offset:64
	v_and_or_b32 v2, v70, 61, v210
	v_cndmask_b32_e32 v2, v2, v70, vcc
	v_lshl_or_b32 v2, v2, 5, v69
	v_ashrrev_i32_e32 v3, 31, v2
	v_lshlrev_b64 v[2:3], 2, v[2:3]
	v_lshl_add_u64 v[4:5], s[34:35], 0, v[2:3]
	v_lshl_add_u64 v[2:3], s[36:37], 0, v[2:3]
	global_load_dword v228, v[4:5], off
	v_cmp_gt_i32_e32 vcc, s33, v68
	global_load_dword v229, v[2:3], off
	s_waitcnt vmcnt(8)
	v_mul_f32_e32 v2, v13, v231
	v_fma_f32 v2, v29, v230, -v2
	v_mul_f32_e32 v5, v29, v231
	v_mul_f32_e32 v2, 0x3dd53b94, v2
	v_fmac_f32_e32 v5, v13, v230
	v_cvt_pk_bf16_f32 v6, v2, s0
	v_mad_i64_i32 v[2:3], s[0:1], v72, s85, v[66:67]
	v_mul_f32_e32 v4, 0x3dd53b94, v5
	s_nop 0
	v_cvt_pk_bf16_f32 v4, v4, s0
	global_store_short v[2:3], v6, off
	global_store_short v[2:3], v4, off offset:64
	v_and_or_b32 v2, v68, 62, v210
	v_cndmask_b32_e32 v2, v2, v68, vcc
	v_lshl_or_b32 v2, v2, 5, v69
	v_ashrrev_i32_e32 v3, 31, v2
	v_lshlrev_b64 v[2:3], 2, v[2:3]
	v_lshl_add_u64 v[4:5], s[34:35], 0, v[2:3]
	v_lshl_add_u64 v[2:3], s[36:37], 0, v[2:3]
	global_load_dword v230, v[4:5], off
	v_cmp_gt_i32_e32 vcc, s33, v0
	global_load_dword v231, v[2:3], off
	s_waitcnt vmcnt(8)
	v_mul_f32_e32 v2, v14, v233
	v_fma_f32 v2, v30, v232, -v2
	v_mul_f32_e32 v5, v30, v233
	v_mul_f32_e32 v2, 0x3dd53b94, v2
	v_fmac_f32_e32 v5, v14, v232
	v_cvt_pk_bf16_f32 v6, v2, s0
	v_mad_i64_i32 v[2:3], s[0:1], v71, s85, v[66:67]
	v_mul_f32_e32 v4, 0x3dd53b94, v5
	s_nop 0
	v_cvt_pk_bf16_f32 v4, v4, s0
	global_store_short v[2:3], v6, off
	global_store_short v[2:3], v4, off offset:64
	v_and_or_b32 v2, v0, 63, v210
	v_cndmask_b32_e32 v2, v2, v0, vcc
	v_lshl_or_b32 v2, v2, 5, v69
	v_ashrrev_i32_e32 v3, 31, v2
	v_lshlrev_b64 v[2:3], 2, v[2:3]
	v_lshl_add_u64 v[4:5], s[34:35], 0, v[2:3]
	v_lshl_add_u64 v[2:3], s[36:37], 0, v[2:3]
	global_load_dword v232, v[4:5], off
	s_nop 0
	global_load_dword v233, v[2:3], off
	s_waitcnt vmcnt(8)
	v_mul_f32_e32 v2, v15, v229
	v_fma_f32 v2, v31, v228, -v2
	v_mul_f32_e32 v5, v31, v229
	v_mul_f32_e32 v2, 0x3dd53b94, v2
	v_fmac_f32_e32 v5, v15, v228
	v_cvt_pk_bf16_f32 v6, v2, s0
	v_mad_i64_i32 v[2:3], s[0:1], v70, s85, v[66:67]
	v_mul_f32_e32 v4, 0x3dd53b94, v5
	s_nop 0
	v_cvt_pk_bf16_f32 v4, v4, s0
	global_store_short v[2:3], v6, off
	global_store_short v[2:3], v4, off offset:64
	s_waitcnt vmcnt(6)
	v_mul_f32_e32 v2, v16, v231
	v_fma_f32 v2, v32, v230, -v2
	v_mul_f32_e32 v5, v32, v231
	v_mul_f32_e32 v2, 0x3dd53b94, v2
	v_fmac_f32_e32 v5, v16, v230
	v_cvt_pk_bf16_f32 v6, v2, s0
	v_mad_i64_i32 v[2:3], s[0:1], v68, s85, v[66:67]
	v_mul_f32_e32 v4, 0x3dd53b94, v5
	s_nop 0
	v_cvt_pk_bf16_f32 v4, v4, s0
	global_store_short v[2:3], v6, off
	global_store_short v[2:3], v4, off offset:64
	s_waitcnt vmcnt(4)
	v_mul_f32_e32 v2, v17, v233
	v_fma_f32 v2, v33, v232, -v2
	v_mul_f32_e32 v2, 0x3dd53b94, v2
	v_cvt_pk_bf16_f32 v6, v2, s0
	v_mad_i64_i32 v[2:3], s[0:1], v0, s85, v[66:67]
	v_mul_f32_e32 v0, v33, v233
	v_fmac_f32_e32 v0, v17, v232
	v_mul_f32_e32 v0, 0x3dd53b94, v0
	v_cvt_pk_bf16_f32 v0, v0, s0
	global_store_short v[2:3], v6, off
	global_store_short v[2:3], v0, off offset:64
	s_branch .LBB0_548
